# half-tile rounds: workgroup c takes tile (c&7)+8*(c>>4), row half bit 3, so a tile's XCD slot in the swizzled order is the workgroup's own XCD (L2 sharing of A rows restored in the half round)
# baseline (speedup 1.0000x reference)
.LBB0_53:
	s_add_i32 s52, s52, 1
	s_mul_i32 s4, s52, s50
	s_mul_hi_u32 s5, s52, s0
	s_add_i32 s5, s5, s4
	s_mul_i32 s4, s52, s0
	v_readlane_b32 s99, v255, 41
	s_cmp_eq_u32 s52, 8
	s_cselect_b32 s99, s99, 0
	s_and_b32 vcc_lo, s1, 7
	s_lshr_b32 s98, s1, 4
	s_lshl3_add_u32 s98, s98, vcc_lo
	s_cmp_lg_u32 s99, 0
	s_cselect_b32 s98, s98, s1
	s_add_u32 s10, s4, s98
	s_addc_u32 s11, s5, s51
	v_mov_b64_e32 v[2:3], 0x83f
	v_cmp_gt_i64_e64 s[4:5], s[10:11], v[2:3]
	s_mov_b64 s[6:7], s[34:35]
	s_mov_b64 s[8:9], s[30:31]
	s_mov_b32 s12, s24
	s_mov_b32 s13, s22
	s_and_b64 vcc, exec, s[4:5]
	s_cbranch_vccnz .LBB0_55
	s_ashr_i32 s14, s10, 31
	s_lshr_b32 s14, s14, 29
	s_add_i32 s14, s10, s14
	s_ashr_i32 s15, s14, 3
	s_and_b32 s14, s14, -8
	s_sub_i32 s14, s10, s14
	s_cmp_lt_i32 s14, 0
	s_movk_i32 s16, 0x109
	s_cselect_b32 s16, s16, 0x108
	s_mul_i32 s14, s16, s14
	s_add_i32 s14, s14, s15
	s_mul_hi_i32 s15, s14, 0x2e8ba2e9
	s_lshr_b32 s16, s15, 31
	s_ashr_i32 s15, s15, 4
	s_add_i32 s15, s15, s16
	s_lshl_b32 s16, s15, 2
	s_sub_i32 s17, 0x60, s16
	s_min_i32 s17, s17, 4
	s_abs_i32 s22, s17
	v_cvt_f32_u32_e32 v0, s22
	s_sub_i32 s24, 0, s22
	s_mulk_i32 s15, 0x58
	s_sub_i32 s14, s14, s15
	v_rcp_iflag_f32_e32 v0, v0
	s_abs_i32 s15, s14
	s_xor_b32 s23, s14, s17
	s_ashr_i32 s23, s23, 31
	v_mul_f32_e32 v0, 0x4f7ffffe, v0
	v_cvt_u32_f32_e32 v0, v0
	s_nop 0
	v_readfirstlane_b32 s25, v0
	s_mul_i32 s24, s24, s25
	s_mul_hi_u32 s24, s25, s24
	s_add_i32 s25, s25, s24
	s_mul_hi_u32 s24, s15, s25
	s_mul_i32 s25, s24, s22
	s_sub_i32 s15, s15, s25
	s_add_i32 s30, s24, 1
	s_sub_i32 s25, s15, s22
	s_cmp_ge_u32 s15, s22
	s_cselect_b32 s24, s30, s24
	s_cselect_b32 s15, s25, s15
	s_add_i32 s25, s24, 1
	s_cmp_ge_u32 s15, s22
	s_cselect_b32 s15, s25, s24
	s_xor_b32 s15, s15, s23
	s_sub_i32 s22, s15, s23
	s_mul_i32 s15, s22, s17
	s_sub_i32 s14, s14, s15
	s_add_i32 s24, s14, s16
.LBB0_55:
	v_mov_b64_e32 v[2:3], 0x840
	s_ashr_i32 s25, s24, 31
	v_cmp_lt_i64_e32 vcc, s[10:11], v[2:3]
	s_lshl_b64 s[10:11], s[24:25], 19
	v_readlane_b32 s14, v254, 33
	v_readlane_b32 s15, v254, 34
	s_add_u32 s34, s14, s10
	s_addc_u32 s35, s15, s11
	v_readlane_b32 s98, v254, 0
	s_bfe_u32 s98, s98, 0x10003
	s_and_b32 s98, s98, s99
	s_mul_i32 s98, s98, 0x40000
	s_add_u32 s34, s34, s98
	s_addc_u32 s35, s35, 0
	s_and_b64 s[10:11], vcc, exec
	s_cselect_b32 s14, s35, s7
	s_cselect_b32 s15, s34, s6
	s_ashr_i32 s23, s22, 31
	s_lshl_b64 s[10:11], s[22:23], 19
	s_add_u32 s30, s3, s10
	s_addc_u32 s31, s42, s11
	s_and_b64 s[10:11], vcc, exec
	s_cselect_b32 s16, s31, s9
	s_cselect_b32 s17, s30, s8
	s_add_u32 s23, s8, 0x100
	s_addc_u32 s25, s9, 0
	s_add_u32 s6, s6, 0x40080
	v_mov_b32_e32 v2, 0
	s_addc_u32 s7, s7, 0
	s_mov_b32 s40, -2
	v_mov_b32_e32 v3, v2
	v_mov_b32_e32 v4, v2
	v_mov_b32_e32 v5, v2
	v_mov_b32_e32 v6, v2
	v_mov_b32_e32 v7, v2
	v_mov_b32_e32 v8, v2
	v_mov_b32_e32 v9, v2
	v_mov_b32_e32 v18, v2
	v_mov_b32_e32 v19, v2
	v_mov_b32_e32 v20, v2
	v_mov_b32_e32 v21, v2
	v_mov_b32_e32 v22, v2
	v_mov_b32_e32 v23, v2
	v_mov_b32_e32 v24, v2
	v_mov_b32_e32 v25, v2
	v_mov_b32_e32 v30, v2
	v_mov_b32_e32 v31, v2
	v_mov_b32_e32 v32, v2
	v_mov_b32_e32 v33, v2
	v_mov_b32_e32 v38, v2
	v_mov_b32_e32 v39, v2
	v_mov_b32_e32 v40, v2
	v_mov_b32_e32 v41, v2
	v_mov_b32_e32 v46, v2
	v_mov_b32_e32 v47, v2
	v_mov_b32_e32 v48, v2
	v_mov_b32_e32 v49, v2
	v_mov_b32_e32 v54, v2
	v_mov_b32_e32 v55, v2
	v_mov_b32_e32 v56, v2
	v_mov_b32_e32 v57, v2
	v_mov_b32_e32 v10, v2
	v_mov_b32_e32 v11, v2
	v_mov_b32_e32 v12, v2
	v_mov_b32_e32 v13, v2
	v_mov_b32_e32 v14, v2
	v_mov_b32_e32 v15, v2
	v_mov_b32_e32 v16, v2
	v_mov_b32_e32 v17, v2
	v_mov_b32_e32 v26, v2
	v_mov_b32_e32 v27, v2
	v_mov_b32_e32 v28, v2
	v_mov_b32_e32 v29, v2
	v_mov_b32_e32 v34, v2
	v_mov_b32_e32 v35, v2
	v_mov_b32_e32 v36, v2
	v_mov_b32_e32 v37, v2
	v_mov_b32_e32 v42, v2
	v_mov_b32_e32 v43, v2
	v_mov_b32_e32 v44, v2
	v_mov_b32_e32 v45, v2
	v_mov_b32_e32 v50, v2
	v_mov_b32_e32 v51, v2
	v_mov_b32_e32 v52, v2
	v_mov_b32_e32 v53, v2
	v_mov_b32_e32 v58, v2
	v_mov_b32_e32 v59, v2
	v_mov_b32_e32 v60, v2
	v_mov_b32_e32 v61, v2
	v_mov_b32_e32 v62, v2
	v_mov_b32_e32 v63, v2
	v_mov_b32_e32 v64, v2
	v_mov_b32_e32 v65, v2
	v_mov_b32_e32 v98, v2
	v_mov_b32_e32 v99, v2
	v_mov_b32_e32 v100, v2
	v_mov_b32_e32 v101, v2
	v_mov_b32_e32 v102, v2
	v_mov_b32_e32 v103, v2
	v_mov_b32_e32 v104, v2
	v_mov_b32_e32 v105, v2
	v_mov_b32_e32 v114, v2
	v_mov_b32_e32 v115, v2
	v_mov_b32_e32 v116, v2
	v_mov_b32_e32 v117, v2
	v_mov_b32_e32 v118, v2
	v_mov_b32_e32 v119, v2
	v_mov_b32_e32 v120, v2
	v_mov_b32_e32 v121, v2
	v_mov_b32_e32 v126, v2
	v_mov_b32_e32 v127, v2
	v_mov_b32_e32 v128, v2
	v_mov_b32_e32 v129, v2
	v_mov_b32_e32 v134, v2
	v_mov_b32_e32 v135, v2
	v_mov_b32_e32 v136, v2
	v_mov_b32_e32 v137, v2
	v_mov_b32_e32 v142, v2
	v_mov_b32_e32 v143, v2
	v_mov_b32_e32 v144, v2
	v_mov_b32_e32 v145, v2
	v_mov_b32_e32 v150, v2
	v_mov_b32_e32 v151, v2
	v_mov_b32_e32 v152, v2
	v_mov_b32_e32 v153, v2
	v_mov_b32_e32 v106, v2
	v_mov_b32_e32 v107, v2
	v_mov_b32_e32 v108, v2
	v_mov_b32_e32 v109, v2
	v_mov_b32_e32 v110, v2
	v_mov_b32_e32 v111, v2
	v_mov_b32_e32 v112, v2
	v_mov_b32_e32 v113, v2
	v_mov_b32_e32 v122, v2
	v_mov_b32_e32 v123, v2
	v_mov_b32_e32 v124, v2
	v_mov_b32_e32 v125, v2
	v_mov_b32_e32 v130, v2
	v_mov_b32_e32 v131, v2
	v_mov_b32_e32 v132, v2
	v_mov_b32_e32 v133, v2
	v_mov_b32_e32 v138, v2
	v_mov_b32_e32 v139, v2
	v_mov_b32_e32 v140, v2
	v_mov_b32_e32 v141, v2
	v_mov_b32_e32 v146, v2
	v_mov_b32_e32 v147, v2
	v_mov_b32_e32 v148, v2
	v_mov_b32_e32 v149, v2
	v_mov_b32_e32 v154, v2
	v_mov_b32_e32 v155, v2
	v_mov_b32_e32 v156, v2
	v_mov_b32_e32 v157, v2
	v_mov_b32_e32 v158, v2
	v_mov_b32_e32 v159, v2
	v_mov_b32_e32 v160, v2
	v_mov_b32_e32 v161, v2
	v_readlane_b32 s99, v255, 41
	s_cmp_eq_u32 s52, 9
	s_cselect_b32 s99, s99, 0

.Lfu_skip8:
	s_setprio 0
	s_add_i32 s40, s40, 2
	s_add_u32 s23, s23, 0x100
	s_addc_u32 s25, s25, 0
	s_add_u32 s6, s6, 0x100
	s_addc_u32 s7, s7, 0
	s_cmp_gt_u32 s40, 13
	s_barrier
	s_cbranch_scc0 .LBB0_56
	v_mov_b32_e32 v0, v163
	v_mov_b32_e32 v186, v1
	v_lshrrev_b32_e32 v66, 1, v0
	v_and_b32_e32 v66, 0x78, v66
	v_lshl_or_b32 v184, s13, 7, v66
	v_ashrrev_i32_e32 v185, 31, v184
	v_lshlrev_b64 v[66:67], 2, v[184:185]
	v_lshl_add_u64 v[70:71], s[26:27], 0, v[66:67]
	v_lshl_add_u64 v[74:75], s[36:37], 0, v[66:67]
	v_lshl_add_u64 v[78:79], s[38:39], 0, v[66:67]
	v_lshl_add_u64 v[94:95], s[28:29], 0, v[66:67]
	global_load_dwordx4 v[66:69], v[70:71], off offset:16
	global_load_dwordx4 v[82:85], v[70:71], off
	s_nop 0
	global_load_dwordx4 v[70:73], v[74:75], off offset:16
	global_load_dwordx4 v[86:89], v[74:75], off
	s_nop 0
	global_load_dwordx4 v[74:77], v[78:79], off offset:16
	global_load_dwordx4 v[90:93], v[78:79], off
	s_nop 0
	global_load_dwordx4 v[78:81], v[94:95], off offset:16
	s_nop 0
	global_load_dwordx4 v[94:97], v[94:95], off
	v_and_b32_e32 v230, 15, v0
	v_ashrrev_i32_e32 v0, 2, v0
	v_and_b32_e32 v0, 0xffffffc0, v0
	v_mov_b32_e32 v187, v1
	v_mov_b32_e32 v194, v1
	v_mov_b32_e32 v195, v1
	v_mov_b32_e32 v198, v1
	v_mov_b32_e32 v199, v1
	v_mov_b32_e32 v190, v1
	v_mov_b32_e32 v191, v1
	v_lshl_add_u32 v231, s12, 8, v0
	v_readlane_b32 s98, v254, 0
	s_bfe_u32 s98, s98, 0x10003
	s_and_b32 s98, s98, s99
	s_lshl_b32 s98, s98, 7
	v_add_u32_e32 v231, s98, v231
	v_mov_b32_dpp v186, v134 row_ror:15 row_mask:0xf bank_mask:0xf
	v_mov_b32_e32 v188, v1
	v_mov_b32_dpp v187, v135 row_ror:15 row_mask:0xf bank_mask:0xf
	v_mov_b32_e32 v189, v1
	v_mov_b32_dpp v194, v136 row_ror:15 row_mask:0xf bank_mask:0xf
	v_mov_b32_e32 v196, v1
	v_mov_b32_dpp v195, v137 row_ror:15 row_mask:0xf bank_mask:0xf
	v_mov_b32_e32 v197, v1
	v_mov_b32_dpp v198, v126 row_ror:15 row_mask:0xf bank_mask:0xf
	v_mov_b32_e32 v200, v1
	v_mov_b32_dpp v199, v127 row_ror:15 row_mask:0xf bank_mask:0xf
	v_mov_b32_e32 v201, v1
	v_mov_b32_dpp v190, v128 row_ror:15 row_mask:0xf bank_mask:0xf
	v_mov_b32_e32 v192, v1
	v_mov_b32_dpp v191, v129 row_ror:15 row_mask:0xf bank_mask:0xf
	v_mov_b32_e32 v193, v1
	v_or_b32_e32 v0, v231, v230
	v_mov_b32_dpp v188, v150 row_shr:1 row_mask:0xf bank_mask:0xf
	v_mov_b32_dpp v186, v150 row_shl:1 row_mask:0xf bank_mask:0xf
	v_mov_b32_dpp v189, v151 row_shr:1 row_mask:0xf bank_mask:0xf
	v_mov_b32_dpp v187, v151 row_shl:1 row_mask:0xf bank_mask:0xf
	v_mov_b32_dpp v196, v152 row_shr:1 row_mask:0xf bank_mask:0xf
	v_mov_b32_dpp v194, v152 row_shl:1 row_mask:0xf bank_mask:0xf
	v_mov_b32_dpp v197, v153 row_shr:1 row_mask:0xf bank_mask:0xf
	v_mov_b32_dpp v195, v153 row_shl:1 row_mask:0xf bank_mask:0xf
	v_mov_b32_dpp v200, v142 row_shr:1 row_mask:0xf bank_mask:0xf
	v_mov_b32_dpp v198, v142 row_shl:1 row_mask:0xf bank_mask:0xf
	v_mov_b32_dpp v201, v143 row_shr:1 row_mask:0xf bank_mask:0xf
	v_mov_b32_dpp v199, v143 row_shl:1 row_mask:0xf bank_mask:0xf
	v_mov_b32_dpp v192, v144 row_shr:1 row_mask:0xf bank_mask:0xf
	v_mov_b32_dpp v190, v144 row_shl:1 row_mask:0xf bank_mask:0xf
	v_mov_b32_dpp v193, v145 row_shr:1 row_mask:0xf bank_mask:0xf
	v_mov_b32_dpp v191, v145 row_shl:1 row_mask:0xf bank_mask:0xf
	v_cmp_eq_u32_e64 s[6:7], 0, v230
	v_cmp_ne_u32_e64 s[10:11], 0, v230
	s_and_saveexec_b64 s[8:9], s[10:11]
	s_cbranch_execz .LBB0_59
	s_waitcnt vmcnt(0)
	v_pk_fma_f32 v[200:201], v[66:67], v[200:201], v[78:79]
	v_pk_fma_f32 v[196:197], v[84:85], v[196:197], v[96:97]
	v_pk_fma_f32 v[200:201], v[142:143], v[70:71], v[200:201]
	v_pk_fma_f32 v[196:197], v[152:153], v[88:89], v[196:197]
	v_pk_fma_f32 v[198:199], v[74:75], v[198:199], v[200:201]
	v_pk_fma_f32 v[194:195], v[92:93], v[194:195], v[196:197]
	v_mul_f32_e32 v172, 0xbfb8aa3b, v198
	v_exp_f32_e32 v172, v172
	v_mul_f32_e32 v173, 0xbfb8aa3b, v199
	v_exp_f32_e32 v173, v173
	v_pk_fma_f32 v[188:189], v[82:83], v[188:189], v[94:95]
	v_add_f32_e32 v172, 1.0, v172
	v_rcp_f32_e32 v200, v172
	v_add_f32_e32 v173, 1.0, v173
	v_mul_f32_e32 v172, 0xbfb8aa3b, v194
	v_rcp_f32_e32 v201, v173
	v_exp_f32_e32 v172, v172
	v_mul_f32_e32 v173, 0xbfb8aa3b, v195
	v_exp_f32_e32 v173, v173
	v_pk_mul_f32 v[198:199], v[198:199], v[200:201]
	v_add_f32_e32 v172, 1.0, v172
	v_pk_fma_f32 v[188:189], v[150:151], v[86:87], v[188:189]
	v_pk_mul_f32 v[196:197], v[154:155], v[198:199]
	v_rcp_f32_e32 v198, v172
	v_add_f32_e32 v172, 1.0, v173
	v_pk_fma_f32 v[186:187], v[90:91], v[186:187], v[188:189]
	v_rcp_f32_e32 v199, v172
	v_mul_f32_e32 v172, 0xbfb8aa3b, v186
	v_exp_f32_e32 v172, v172
	v_mul_f32_e32 v173, 0xbfb8aa3b, v187
	v_exp_f32_e32 v173, v173
	v_pk_fma_f32 v[192:193], v[68:69], v[192:193], v[80:81]
	v_add_f32_e32 v172, 1.0, v172
	v_pk_fma_f32 v[192:193], v[144:145], v[72:73], v[192:193]
	v_pk_mul_f32 v[188:189], v[194:195], v[198:199]
	v_pk_fma_f32 v[190:191], v[76:77], v[190:191], v[192:193]
	v_rcp_f32_e32 v194, v172
	v_add_f32_e32 v172, 1.0, v173
	v_mul_f32_e32 v173, 0xbfb8aa3b, v190
	v_exp_f32_e32 v173, v173
	v_mul_f32_e32 v174, 0xbfb8aa3b, v191
	v_exp_f32_e32 v174, v174
	v_rcp_f32_e32 v195, v172
	v_add_f32_e32 v172, 1.0, v173
	v_rcp_f32_e32 v192, v172
	v_add_f32_e32 v172, 1.0, v174
	v_rcp_f32_e32 v193, v172
	v_readlane_b32 s12, v254, 35
	v_readlane_b32 s13, v254, 36
	v_pk_mul_f32 v[186:187], v[186:187], v[194:195]
	v_pk_mul_f32 v[190:191], v[190:191], v[192:193]
	v_mov_b64_e32 v[192:193], s[12:13]
	s_movk_i32 s12, 0x1600
	v_pk_mul_f32 v[188:189], v[160:161], v[188:189]
	v_pk_mul_f32 v[186:187], v[158:159], v[186:187]
	v_pk_mul_f32 v[190:191], v[156:157], v[190:191]
	v_mad_i64_i32 v[192:193], s[12:13], v0, s12, v[192:193]
	v_lshl_add_u64 v[192:193], v[184:185], 1, v[192:193]
	v_cvt_pk_bf16_f32 v186, v186, v187
	v_cvt_pk_bf16_f32 v187, v188, v189
	v_cvt_pk_bf16_f32 v188, v196, v197
	v_cvt_pk_bf16_f32 v189, v190, v191
	global_store_dwordx4 v[192:193], v[186:189], off

.LBB0_1240:
	s_add_i32 s36, s36, 1
	s_mul_i32 s4, s36, s35
	s_mul_hi_u32 s5, s36, s0
	s_add_i32 s5, s5, s4
	s_mul_i32 s4, s36, s0
	v_readlane_b32 s99, v255, 41
	s_cmp_eq_u32 s36, 1
	s_cselect_b32 s99, s99, 0
	s_and_b32 vcc_lo, s1, 7
	s_lshr_b32 s98, s1, 4
	s_lshl3_add_u32 s98, s98, vcc_lo
	s_cmp_lg_u32 s99, 0
	s_cselect_b32 s98, s98, s1
	s_add_u32 s8, s4, s98
	s_addc_u32 s9, s5, s24
	v_cmp_gt_i64_e64 s[4:5], s[8:9], v[164:165]
	v_cmp_lt_i64_e64 s[6:7], s[8:9], v[166:167]
	s_and_b64 vcc, exec, s[4:5]
	s_cbranch_vccnz .LBB0_1242
	s_ashr_i32 s9, s8, 31
	s_lshr_b32 s9, s9, 29
	s_add_i32 s9, s8, s9
	s_ashr_i32 s18, s9, 3
	s_and_b32 s9, s9, -8
	s_sub_i32 s8, s8, s9
	s_cmp_lt_i32 s8, 0
	s_cselect_b32 s9, 49, 48
	s_mul_i32 s8, s9, s8
	s_add_i32 s8, s8, s18
	s_ashr_i32 s9, s8, 31
	s_lshr_b32 s9, s9, 28
	s_add_i32 s9, s8, s9
	s_ashr_i32 s18, s9, 4
	s_lshl_b32 s18, s18, 2
	s_sub_i32 s19, 0x60, s18
	s_min_i32 s19, s19, 4
	s_abs_i32 s20, s19
	v_cvt_f32_u32_e32 v2, s20
	s_sub_i32 s37, 0, s20
	s_and_b32 s9, s9, -16
	s_sub_i32 s8, s8, s9
	v_rcp_iflag_f32_e32 v2, v2
	s_abs_i32 s9, s8
	s_xor_b32 s21, s8, s19
	s_ashr_i32 s21, s21, 31
	v_mul_f32_e32 v2, 0x4f7ffffe, v2
	v_cvt_u32_f32_e32 v2, v2
	s_nop 0
	v_readfirstlane_b32 s38, v2
	s_mul_i32 s37, s37, s38
	s_mul_hi_u32 s37, s38, s37
	s_add_i32 s38, s38, s37
	s_mul_hi_u32 s37, s9, s38
	s_mul_i32 s38, s37, s20
	s_sub_i32 s9, s9, s38
	s_add_i32 s41, s37, 1
	s_sub_i32 s38, s9, s20
	s_cmp_ge_u32 s9, s20
	s_cselect_b32 s37, s41, s37
	s_cselect_b32 s9, s38, s9
	s_add_i32 s38, s37, 1
	s_cmp_ge_u32 s9, s20
	s_cselect_b32 s9, s38, s37
	s_xor_b32 s9, s9, s21
	s_sub_i32 s37, s9, s21
	s_mul_i32 s9, s37, s19
	s_sub_i32 s8, s8, s9
	s_add_i32 s38, s8, s18
.LBB0_1242:
	v_cndmask_b32_e64 v2, 0, 1, s[6:7]
	v_cmp_ne_u32_e64 s[8:9], 1, v2
	s_andn2_b64 vcc, exec, s[6:7]
	s_mov_b64 s[6:7], s[14:15]
	s_cbranch_vccnz .LBB0_1244
	s_mul_i32 s6, s38, 0x160000
	v_readlane_b32 s18, v254, 35
	s_mul_hi_i32 s7, s38, 0x160000
	v_readlane_b32 s19, v254, 36
	s_add_u32 s6, s18, s6
	s_addc_u32 s7, s19, s7
	v_readlane_b32 s98, v254, 0
	s_bfe_u32 s98, s98, 0x10003
	s_and_b32 s98, s98, s99
	s_mul_i32 s98, s98, 0xb0000
	s_add_u32 s6, s6, s98
	s_addc_u32 s7, s7, 0

.Lfd_skip8:
	s_setprio 0
	s_add_i32 s43, s43, 2
	s_add_u32 s41, s41, 0x100
	s_addc_u32 s42, s42, 0
	s_cmp_gt_u32 s43, 41
	s_mov_b64 s[14:15], s[16:17]
	s_barrier
	s_cbranch_scc0 .LBB0_1247
	v_mov_b32_e32 v154, v163
	s_lshl_b32 s14, s39, 8
	v_readlane_b32 s98, v254, 0
	s_bfe_u32 s98, s98, 0x10003
	s_and_b32 s98, s98, s99
	s_lshl_b32 s98, s98, 7
	s_add_i32 s14, s14, s98
	v_ashrrev_i32_e32 v99, 2, v154
	v_and_b32_e32 v99, 0xffffffc0, v99
	v_add_u32_e32 v155, s14, v99
	s_addk_i32 s14, 0xe000
	s_lshr_b32 s14, s14, 11
	s_lshl_b32 s15, s40, 8
	v_lshrrev_b32_e32 v99, 1, v154
	s_add_i32 s16, s14, 1
	v_and_b32_e32 v98, 0xc0, v154
	v_and_b32_e32 v99, 24, v99
	s_cmp_gt_i32 s39, 31
	v_or3_b32 v152, v98, s15, v99
	s_cselect_b64 s[14:15], -1, 0
	s_and_b64 vcc, s[14:15], exec
	s_cselect_b32 s14, s16, 0
	s_mul_hi_u32 s15, s14, 0x6000
	s_mulk_i32 s14, 0x6000
	s_add_u32 s14, s29, s14
	s_addc_u32 s15, s30, s15
	v_ashrrev_i32_e32 v153, 31, v152
	v_lshl_add_u64 v[106:107], v[152:153], 2, s[14:15]
	global_load_dwordx4 v[102:105], v[106:107], off offset:16
	global_load_dwordx4 v[110:113], v[106:107], off
	global_load_dwordx4 v[98:101], v[106:107], off offset:144
	s_nop 0
	global_load_dwordx4 v[106:109], v[106:107], off offset:128
	v_and_or_b32 v154, v154, 15, v155
	s_mov_b64 s[14:15], -1
	v_ashrrev_i32_e32 v155, 31, v154
	s_cbranch_vccz .LBB0_1250
	v_lshlrev_b64 v[158:159], 12, v[154:155]
	s_mov_b32 s14, 0xfe000000
	v_lshl_add_u64 v[156:157], s[12:13], 0, v[158:159]
	s_mov_b32 s15, -1
	v_lshl_add_u64 v[156:157], v[156:157], 0, s[14:15]
	s_mov_b64 s[14:15], 0
